# cumulative: setprio-pair removal + duplicate post-barrier waits removed + scan pk_mul split + obsolete scan nops removed + loop-head alignment
# baseline (speedup 1.0000x reference)
; DI void phase_scan(int wid0, const Params& p, unsigned char* lds, bool dry) {
;     ...
;             const unsigned vao = vs_base + (unsigned)(cur * 9216 + (8 * l4 + (l15 >> 2)) * 144 + 2 * (16 * cb0 + 4 * (l15 & 3)));
;             const unsigned vau = vs_base + (unsigned)(cur * 9216 + (8 * hi + (l15 >> 2)) * 144 + 2 * (16 * ((lane >> 4) & 1) + 4 * (l15 & 3)));
;             s16x4 ol[2][2], oh[2][2], ul0[4], uh0[4], ul1[4], uh1[4];
; #pragma unroll
;             for (int cc = 0; cc < 2; ++cc)
; #pragma unroll
;                 for (int s = 0; s < 2; ++s) { ol[cc][s] = tr_read0(vao + cc * 32 + s * 32 * 144); oh[cc][s] = tr_read0(vao + cc * 32 + s * 32 * 144 + 4 * 144); }
; #pragma unroll
;             for (int s = 0; s < 2; ++s) {
;                 ul0[s] = tr_read0(vau + s * 16 * 144); uh0[s] = tr_read0(vau + s * 16 * 144 + 4 * 144);
;                 ul1[s] = tr_read0(vau + s * 16 * 144 + 64); uh1[s] = tr_read0(vau + s * 16 * 144 + 4 * 144 + 64);
;             }
;             {
;                 __builtin_amdgcn_sched_barrier(0);
;                 f32x4 oacc[2];
; #pragma unroll
;                 for (int cc = 0; cc < 2; ++cc) {
;                     const int cb = cb0 + cc; oacc[cc] = (f32x4){0.f, 0.f, 0.f, 0.f};
; #pragma unroll
;                     for (int s = 0; s < 2; ++s) oacc[cc] = MFMA16(PK8(ol[cc][s], oh[cc][s]), at[s], oacc[cc]);
;                     const bf16_t* sp = sbt + cur * 16896 + (16 * cb + l15) * 264 + 8 * l4;
; #pragma unroll
;                     for (int s = 0; s < 8; ++s) { const bf16x8 bfr = *(const bf16x8*)(sp + 32 * s); oacc[cc] = MFMA16(bfr, aq[s], oacc[cc]); }
;                 }
; #pragma unroll
;                 for (int s = 2; s < 4; ++s) {
;                     ul0[s] = tr_read0(vau + s * 16 * 144); uh0[s] = tr_read0(vau + s * 16 * 144 + 4 * 144);
;                     ul1[s] = tr_read0(vau + s * 16 * 144 + 64); uh1[s] = tr_read0(vau + s * 16 * 144 + 4 * 144 + 64);
;                 }
; #pragma unroll
;                 for (int cc = 0; cc < 2; ++cc) {
;                     const int col = colv + 16 * (cb0 + cc) + 4 * l4;
;                     u32x2 w; w.x = cvt_pk_bf16(oacc[cc][0], oacc[cc][1]); w.y = cvt_pk_bf16(oacc[cc][2], oacc[cc][3]);
;                     if (dry) {} else if (c > 0) *(u32x2*)(vb + (size_t)(row0 + i) * 2048 + col) = w;
.LBB0_239:
	v_add_u32_e32 v62, s9, v181
	v_add_u32_e32 v179, s9, v180
	ds_read_b64_tr_b16 v[198:199], v62 offset:576
	ds_read_b64_tr_b16 v[196:197], v62
	ds_read_b64_tr_b16 v[202:203], v62 offset:608
	ds_read_b64_tr_b16 v[200:201], v62 offset:32
	ds_read_b64_tr_b16 v[204:205], v62 offset:4608
	ds_read_b64_tr_b16 v[206:207], v62 offset:5184
	ds_read_b64_tr_b16 v[210:211], v62 offset:5216
	ds_read_b64_tr_b16 v[208:209], v62 offset:4640
	ds_read_b64_tr_b16 v[82:83], v179
	ds_read_b64_tr_b16 v[84:85], v179 offset:576
	ds_read_b64_tr_b16 v[80:81], v179 offset:640
	ds_read_b64_tr_b16 v[78:79], v179 offset:64
	ds_read_b64_tr_b16 v[74:75], v179 offset:2304
	ds_read_b64_tr_b16 v[76:77], v179 offset:2880
	ds_read_b64_tr_b16 v[64:65], v179 offset:2944
	ds_read_b64_tr_b16 v[62:63], v179 offset:2368
	s_waitcnt vmcnt(17) lgkmcnt(14)
	v_mfma_f32_16x16x32_bf16 v[196:199], v[196:199], v[118:121], 0
	s_mul_i32 s9, s7, 0x8400
	v_add_u32_e32 v212, s9, v182
	v_add_u32_e32 v213, v212, v145
	s_waitcnt lgkmcnt(12)
	v_mfma_f32_16x16x32_bf16 v[118:121], v[200:203], v[118:121], 0
	v_add_u32_e32 v200, v212, v189
	s_waitcnt vmcnt(0)
	v_mul_f32_e32 v32, v32, v72
	v_mul_f32_e32 v33, v33, v73
	v_mul_f32_e32 v28, v28, v60
	v_mul_f32_e32 v29, v29, v61
	s_waitcnt lgkmcnt(10)
	v_mfma_f32_16x16x32_bf16 v[196:199], v[204:207], v[122:125], v[196:199]
	ds_read_b128 v[214:217], v213
	v_mul_f32_e32 v24, v24, v56
	v_mul_f32_e32 v25, v25, v57
	v_mul_f32_e32 v20, v20, v68
	v_mul_f32_e32 v21, v21, v69
	s_waitcnt lgkmcnt(9)
	v_mfma_f32_16x16x32_bf16 v[118:121], v[208:211], v[122:125], v[118:121]
	ds_read_b128 v[218:221], v200
	v_mul_f32_e32 v18, v18, v66
	v_mul_f32_e32 v19, v19, v67
	v_mul_f32_e32 v30, v30, v70
	v_mul_f32_e32 v31, v31, v71
	ds_read_b128 v[222:225], v213 offset:64
	ds_read_b128 v[226:229], v200 offset:64
	s_waitcnt lgkmcnt(3)
	v_mfma_f32_16x16x32_bf16 v[196:199], v[214:217], v[114:117], v[196:199]
	v_mul_f32_e32 v26, v26, v58
	v_mul_f32_e32 v27, v27, v59
	v_mul_f32_e32 v22, v22, v54
	v_mul_f32_e32 v23, v23, v55
	ds_read_b128 v[236:239], v213 offset:128
	s_waitcnt lgkmcnt(3)
	v_mfma_f32_16x16x32_bf16 v[114:117], v[218:221], v[114:117], v[118:121]
	v_mul_f32_e64 v16, v16, v72
	v_mul_f32_e64 v17, v17, v73
	v_mul_f32_e32 v12, v12, v60
	v_mul_f32_e32 v13, v13, v61
	v_mul_f32_e32 v8, v8, v56
	v_mul_f32_e32 v9, v9, v57
	ds_read_b128 v[240:243], v200 offset:128
	s_waitcnt lgkmcnt(3)
	v_mfma_f32_16x16x32_bf16 v[196:199], v[222:225], v[98:101], v[196:199]
	v_mul_f32_e32 v4, v4, v68
	v_mul_f32_e32 v5, v5, v69
	v_mul_f32_e32 v2, v2, v66
	v_mul_f32_e32 v3, v3, v67
	ds_read_b128 v[248:251], v213 offset:192
	s_waitcnt lgkmcnt(3)
	v_mfma_f32_16x16x32_bf16 v[98:101], v[226:229], v[98:101], v[114:117]
	v_mul_f32_e32 v14, v14, v70
	v_mul_f32_e32 v15, v15, v71
	v_mul_f32_e32 v10, v10, v58
	v_mul_f32_e32 v11, v11, v59
	ds_read_b128 v[252:255], v200 offset:192
	s_waitcnt lgkmcnt(3)
	v_mfma_f32_16x16x32_bf16 v[196:199], v[236:239], v[110:113], v[196:199]
	v_mul_f32_e32 v6, v6, v54
	v_mul_f32_e32 v7, v7, v55
	ds_read_b128 v[214:217], v213 offset:256
	s_waitcnt lgkmcnt(3)
	v_mfma_f32_16x16x32_bf16 v[98:101], v[240:243], v[110:113], v[98:101]
	ds_read_b128 v[218:221], v200 offset:256
	s_waitcnt lgkmcnt(3)
	v_mfma_f32_16x16x32_bf16 v[196:199], v[248:251], v[86:89], v[196:199]
	ds_read_b128 v[222:225], v213 offset:320
	s_waitcnt lgkmcnt(3)
	v_mfma_f32_16x16x32_bf16 v[86:89], v[252:255], v[86:89], v[98:101]
	ds_read_b128 v[226:229], v200 offset:320
	s_waitcnt lgkmcnt(3)
	v_mfma_f32_16x16x32_bf16 v[196:199], v[214:217], v[102:105], v[196:199]
	ds_read_b128 v[236:239], v213 offset:384
	s_waitcnt lgkmcnt(3)
	v_mfma_f32_16x16x32_bf16 v[86:89], v[218:221], v[102:105], v[86:89]
	ds_read_b128 v[240:243], v200 offset:384
	s_waitcnt lgkmcnt(3)
	v_mfma_f32_16x16x32_bf16 v[196:199], v[222:225], v[90:93], v[196:199]
	ds_read_b128 v[248:251], v213 offset:448
	s_waitcnt lgkmcnt(3)
	v_mfma_f32_16x16x32_bf16 v[86:89], v[226:229], v[90:93], v[86:89]
	ds_read_b128 v[252:255], v200 offset:448
	s_waitcnt lgkmcnt(3)
	v_mfma_f32_16x16x32_bf16 v[196:199], v[236:239], v[106:109], v[196:199]
	s_waitcnt lgkmcnt(2)
	v_mfma_f32_16x16x32_bf16 v[86:89], v[240:243], v[106:109], v[86:89]
	v_add_u32_e32 v106, s8, v194
	v_ashrrev_i32_e32 v107, 31, v106
	s_waitcnt lgkmcnt(1)
	v_mfma_f32_16x16x32_bf16 v[196:199], v[248:251], v[94:97], v[196:199]
	v_lshlrev_b64 v[106:107], 12, v[106:107]
	v_lshl_add_u64 v[106:107], s[28:29], 0, v[106:107]
	v_lshl_add_u64 v[110:111], v[106:107], 0, v[0:1]
	s_waitcnt lgkmcnt(0)
	v_mfma_f32_16x16x32_bf16 v[86:89], v[252:255], v[94:97], v[86:89]
	ds_read_b64_tr_b16 v[90:91], v179 offset:4608
	ds_read_b64_tr_b16 v[92:93], v179 offset:5184
	ds_read_b64_tr_b16 v[94:95], v179 offset:4672
	ds_read_b64_tr_b16 v[96:97], v179 offset:5248
	ds_read_b64_tr_b16 v[98:99], v179 offset:6912
	ds_read_b64_tr_b16 v[100:101], v179 offset:7488
	ds_read_b64_tr_b16 v[102:103], v179 offset:6976
	ds_read_b64_tr_b16 v[104:105], v179 offset:7552
	v_mov_b32_e32 v179, v1
	v_cvt_pk_bf16_f32 v108, v196, v197
	v_cvt_pk_bf16_f32 v109, v198, v199
	v_cvt_pk_bf16_f32 v86, v86, v87
	v_cvt_pk_bf16_f32 v87, v88, v89
	v_lshl_add_u64 v[88:89], v[106:107], 0, v[178:179]
	global_store_dwordx2 v[110:111], v[108:109], off
	global_store_dwordx2 v[88:89], v[86:87], off
	v_mfma_f32_32x32x16_bf16 v[18:33], v[50:53], v[82:85], v[18:33]
	s_xor_b32 s7, s7, 1
	s_mul_i32 s7, s7, 0x8400
	s_add_i32 s8, s8, 64
	s_add_i32 s6, s6, 4
	s_add_i32 s2, s2, 1
	s_cmpk_eq_i32 s8, 0x1000
	v_mfma_f32_32x32x16_bf16 v[2:17], v[50:53], v[78:81], v[2:17]
	v_mfma_f32_32x32x16_bf16 v[18:33], v[46:49], v[74:77], v[18:33]
	v_mfma_f32_32x32x16_bf16 v[2:17], v[46:49], v[62:65], v[2:17]
	v_add_u32_e32 v46, s7, v131
	v_add_u32_e32 v47, 0x4000, v46
	s_waitcnt lgkmcnt(6)
	v_mfma_f32_32x32x16_bf16 v[18:33], v[42:45], v[90:93], v[18:33]
	s_waitcnt lgkmcnt(4)
	v_mfma_f32_32x32x16_bf16 v[2:17], v[42:45], v[94:97], v[2:17]
	s_waitcnt lgkmcnt(2)
	v_mfma_f32_32x32x16_bf16 v[18:33], v[38:41], v[98:101], v[18:33]
	s_waitcnt lgkmcnt(0)
	v_mfma_f32_32x32x16_bf16 v[2:17], v[38:41], v[102:105], v[2:17]
	s_nop 9
	v_cvt_pk_bf16_f32 v42, v18, v19
	v_cvt_pk_bf16_f32 v43, v20, v21
	v_cvt_pk_bf16_f32 v40, v22, v23
	v_cvt_pk_bf16_f32 v41, v24, v25
	ds_write2_b64 v46, v[42:43], v[40:41] offset1:2
	v_cvt_pk_bf16_f32 v42, v30, v31
	v_cvt_pk_bf16_f32 v43, v32, v33
	v_cvt_pk_bf16_f32 v38, v2, v3
	v_cvt_pk_bf16_f32 v39, v4, v5
	v_cvt_pk_bf16_f32 v44, v6, v7
	v_cvt_pk_bf16_f32 v45, v8, v9
	ds_write2_b64 v47, v[38:39], v[44:45] offset0:64 offset1:66
	v_cvt_pk_bf16_f32 v38, v26, v27
	v_cvt_pk_bf16_f32 v39, v28, v29
	v_cvt_pk_bf16_f32 v40, v10, v11
	v_cvt_pk_bf16_f32 v41, v12, v13
	v_cvt_pk_bf16_f32 v44, v14, v15
	v_cvt_pk_bf16_f32 v45, v16, v17
	ds_write2_b64 v46, v[38:39], v[42:43] offset0:4 offset1:6
	ds_write2_b64 v47, v[40:41], v[44:45] offset0:68 offset1:70
	s_cbranch_scc1 .LBB0_228
